# same as previous plus unreachable padding so that later code keeps the baseline 256-byte placement
# speedup vs baseline: 1.0065x; 1.0017x over previous
.Lp1r_Bm:
	ds_read_b128 v[106:109], v94 offset:18432
	ds_read_b128 v[110:113], v95 offset:18432
	ds_read_b128 v[114:117], v97
	ds_read_b128 v[118:121], v98
	ds_read_b128 v[122:125], v96
	ds_read_b128 v[126:129], v96 offset:64
	ds_read_b128 v[130:133], v99 offset:2304
	ds_read_b128 v[134:137], v100 offset:2304
	ds_read_b128 v[138:141], v101 offset:4608
	ds_read_b128 v[142:145], v102 offset:4608
	ds_read_b128 v[146:149], v96 offset:128
	ds_read_b128 v[150:153], v96 offset:192
	ds_read_b128 v[154:157], v103 offset:6912
	ds_read_b128 v[158:161], v104 offset:6912
	s_waitcnt lgkmcnt(9)
	v_pk_mul_f32 v[36:37], v[36:37], v[122:123]
	v_pk_mul_f32 v[38:39], v[38:39], v[124:125]
	s_waitcnt lgkmcnt(8)
	v_pk_mul_f32 v[48:49], v[48:49], v[126:127]
	v_pk_mul_f32 v[50:51], v[50:51], v[128:129]
	s_waitcnt lgkmcnt(3)
	v_pk_mul_f32 v[44:45], v[44:45], v[146:147]
	v_pk_mul_f32 v[46:47], v[46:47], v[148:149]
	s_waitcnt lgkmcnt(2)
	v_pk_mul_f32 v[40:41], v[40:41], v[150:151]
	v_pk_mul_f32 v[42:43], v[42:43], v[152:153]
	v_mfma_f32_16x16x32_bf16 v[36:39], v[114:117], v[106:109], v[36:39]
	v_mfma_f32_16x16x32_bf16 v[48:51], v[130:133], v[106:109], v[48:51]
	v_mfma_f32_16x16x32_bf16 v[44:47], v[138:141], v[106:109], v[44:47]
	s_waitcnt lgkmcnt(1)
	v_mfma_f32_16x16x32_bf16 v[40:43], v[154:157], v[106:109], v[40:43]
	v_mfma_f32_16x16x32_bf16 v[36:39], v[118:121], v[110:113], v[36:39]
	v_mfma_f32_16x16x32_bf16 v[48:51], v[134:137], v[110:113], v[48:51]
	v_mfma_f32_16x16x32_bf16 v[44:47], v[142:145], v[110:113], v[44:47]
	s_waitcnt lgkmcnt(0)
	v_mfma_f32_16x16x32_bf16 v[40:43], v[158:161], v[110:113], v[40:43]
	ds_read_b128 v[114:117], v97 offset:9216
	ds_read_b128 v[118:121], v98 offset:9216
	ds_read_b128 v[122:125], v96 offset:256
	ds_read_b128 v[126:129], v96 offset:320
	ds_read_b128 v[130:133], v99 offset:11520
	ds_read_b128 v[134:137], v100 offset:11520
	ds_read_b128 v[138:141], v101 offset:13824
	ds_read_b128 v[142:145], v102 offset:13824
	ds_read_b128 v[146:149], v96 offset:384
	ds_read_b128 v[150:153], v96 offset:448
	ds_read_b128 v[154:157], v103 offset:16128
	ds_read_b128 v[158:161], v104 offset:16128
	s_waitcnt lgkmcnt(9)
	v_pk_mul_f32 v[30:31], v[30:31], v[122:123]
	v_pk_mul_f32 v[32:33], v[32:33], v[124:125]
	s_waitcnt lgkmcnt(8)
	v_pk_mul_f32 v[26:27], v[26:27], v[126:127]
	v_pk_mul_f32 v[28:29], v[28:29], v[128:129]
	s_waitcnt lgkmcnt(3)
	v_pk_mul_f32 v[22:23], v[22:23], v[146:147]
	v_pk_mul_f32 v[24:25], v[24:25], v[148:149]
	s_waitcnt lgkmcnt(2)
	v_pk_mul_f32 v[18:19], v[18:19], v[150:151]
	v_pk_mul_f32 v[20:21], v[20:21], v[152:153]
	v_mfma_f32_16x16x32_bf16 v[30:33], v[114:117], v[106:109], v[30:33]
	v_mfma_f32_16x16x32_bf16 v[26:29], v[130:133], v[106:109], v[26:29]
	v_mfma_f32_16x16x32_bf16 v[22:25], v[138:141], v[106:109], v[22:25]
	s_waitcnt lgkmcnt(1)
	v_mfma_f32_16x16x32_bf16 v[18:21], v[154:157], v[106:109], v[18:21]
	v_mfma_f32_16x16x32_bf16 v[30:33], v[118:121], v[110:113], v[30:33]
	v_mfma_f32_16x16x32_bf16 v[26:29], v[134:137], v[110:113], v[26:29]
	v_mfma_f32_16x16x32_bf16 v[22:25], v[142:145], v[110:113], v[22:25]
	s_waitcnt lgkmcnt(0)
	v_mfma_f32_16x16x32_bf16 v[18:21], v[158:161], v[110:113], v[18:21]
	s_cmp_eq_u32 s14, s7
	s_barrier
	s_cbranch_scc1 .LBB0_838
	s_branch .Lp1r_A
	s_nop 0
	s_nop 0
	s_nop 0
	s_nop 0
	s_nop 0
	s_nop 0
	s_nop 0
	s_nop 0
	s_nop 0
	s_nop 0
	s_nop 0
	s_nop 0
	s_nop 0
	s_nop 0
	s_nop 0
	s_nop 0
	s_nop 0
	s_nop 0
	s_nop 0
	s_nop 0
	s_nop 0
	s_nop 0
	s_nop 0
	s_nop 0
	s_nop 0
	s_nop 0
	s_nop 0
	s_nop 0
	s_nop 0
	s_nop 0
	s_nop 0
	s_nop 0
	s_nop 0
	s_nop 0
	s_nop 0
	s_nop 0
	s_nop 0
	s_nop 0
	s_nop 0
	s_nop 0
	s_nop 0
	s_nop 0
	s_nop 0

.LBB0_1134:
	s_or_b64 exec, exec, s[16:17]
	v_mul_f32_e32 v178, v161, v161
	s_waitcnt lgkmcnt(0)
	v_mul_f32_e32 v179, v163, v163
	v_fmac_f32_e32 v178, v160, v160
	v_fmac_f32_e32 v179, v162, v162
	v_add_f32_e32 v178, v178, v179
	ds_bpermute_b32 v176, v176, v178
	s_waitcnt lgkmcnt(0)
	v_add_f32_e32 v176, v178, v176
	ds_bpermute_b32 v177, v177, v176
	s_and_saveexec_b64 s[16:17], s[42:43]
	s_cbranch_execz .LBB0_1103
	s_waitcnt lgkmcnt(0)
	v_add_f32_e32 v176, v176, v177
	ds_write_b32 v214, v176 offset:192
	s_branch .LBB0_1103
	s_nop 0
	s_nop 0
	s_nop 0
	s_nop 0
	s_nop 0
	s_nop 0
	s_nop 0
	s_nop 0
	s_nop 0
	s_nop 0
